# phase j=2: workgroups bx>=128 run dilated attention before HGRN pass 1 (overlap bandwidth-bound and latency-bound halves)
# baseline (speedup 1.0000x reference)
.LBB0_375:
	s_andn2_b64 vcc, exec, s[0:1]
	s_mov_b64 s[42:43], 0
	s_cbranch_vccnz .LBB0_563
	s_cmp_gt_i32 s83, 1
	s_mov_b64 s[0:1], -1
	s_cbranch_scc0 .LBB0_561
	s_mov_b32 s101, 0
	s_mov_b32 s0, -1
	v_readlane_b32 s2, v250, 34
	v_mbcnt_lo_u32_b32 v0, s0, 0
	v_mbcnt_hi_u32_b32 v0, s0, v0
	v_readlane_b32 s0, v250, 25
	v_readlane_b32 s3, v250, 35
	s_andn2_b64 vcc, exec, s[2:3]
	v_add_u32_e32 v44, s0, v0
	s_mov_b64 s[0:1], -1
	v_and_b32_e32 v65, 15, v44
	v_readlane_b32 s8, v253, 7
	v_readlane_b32 s9, v253, 9
	s_cbranch_vccnz .LBB0_379
	v_and_b32_e32 v45, 15, v44
	s_mov_b64 s[0:1], 0
.LBB0_379:
	s_andn2_b64 vcc, exec, s[0:1]
	s_cbranch_vccnz .LBB0_521
	v_readlane_b32 s0, v250, 0
	s_bitcmp1_b32 s0, 7
	s_cbranch_scc0 .Lsw_hg
	s_mov_b32 s101, 1
	s_branch .LBB0_520
.Lsw_hg:
	s_waitcnt lgkmcnt(0)
	v_and_b32_e32 v1, 0x7f, v44
	v_readlane_b32 s0, v255, 2
	v_readlane_b32 s2, v255, 3
	v_lshlrev_b32_e32 v5, 2, v1
	v_lshl_add_u32 v83, v44, 2, s0
	v_mov_b32_e32 v3, s2
	s_movk_i32 s1, 0x90
	v_add_u32_e32 v84, s0, v5
	s_movk_i32 s0, 0x80
	v_ashrrev_i32_e32 v2, 7, v44
	v_lshlrev_b32_e32 v80, 1, v1
	v_mad_u32_u24 v3, v1, s1, v3
	v_cmp_gt_u32_e64 s[42:43], s0, v44
	v_mad_u32_u24 v1, v1, s1, 0
	v_readlane_b32 s0, v250, 15
	v_lshlrev_b32_e32 v81, 4, v2
	v_lshlrev_b32_e32 v4, 5, v2
	v_cmp_lt_i32_e32 vcc, 0, v2
	v_cmp_lt_i32_e64 s[38:39], 1, v2
	v_cmp_lt_i32_e64 s[40:41], 2, v2
	v_and_b32_e32 v86, 48, v44
	v_mul_u32_u24_e32 v2, 0x90, v65
	v_mov_b32_e32 v45, v64
	v_readlane_b32 s1, v250, 16
	v_and_b32_e32 v0, 63, v44
	v_add3_u32 v88, 0, v86, v2
	v_lshl_add_u64 v[40:41], v[44:45], 2, s[0:1]
	v_readlane_b32 s0, v250, 0
	v_sub_u32_e32 v82, 63, v81
	v_add_u32_e32 v85, s16, v5
	s_movk_i32 s25, 0x90
	v_add_u32_e32 v87, s2, v86
	v_add_u32_e32 v89, 0xee00, v88
	v_lshlrev_b32_e32 v42, 2, v0
	v_add_u32_e32 v45, v3, v4
	v_add_u32_e32 v90, v1, v4
	s_mov_b32 s2, s0
	s_mov_b32 s8, s0
	s_branch .LBB0_383

.LBB0_520:
	s_cmp_eq_u32 s101, 2
	s_cbranch_scc1 .Lsw_end
	v_mov_b32_e32 v45, v65
	v_readlane_b32 s8, v253, 7
	v_readlane_b32 s9, v253, 9

.Lsw_end:
	s_mov_b32 s101, 0
	s_branch .LBB0_560
.Lsw_back:
	s_mov_b32 s101, 2
	s_waitcnt lgkmcnt(0)
	s_barrier
	s_mov_b32 s0, -1
	s_nop 0
	v_mbcnt_lo_u32_b32 v0, s0, 0
	v_mbcnt_hi_u32_b32 v0, s0, v0
	v_readlane_b32 s0, v250, 25
	s_nop 1
	v_add_u32_e32 v44, s0, v0
	v_and_b32_e32 v65, 15, v44
	s_branch .Lsw_hg
.LBB0_560:
	s_cmp_eq_u32 s101, 1
	s_cbranch_scc1 .Lsw_back
	s_mov_b64 s[0:1], 0
